# W_o phase: workgroups 0-63 run their sample K-slice task before their prompt tile (same staggering of the residual epilogues as the FFN down phase)
# speedup vs baseline: 1.0129x; 1.0023x over previous
; __device__ __forceinline__ int bidx() { int b = blockIdx.x; asm volatile("" : "+s"(b)); return b; }
; #define INP(p, i) ldp((p).tbl, i)
; __device__ __forceinline__ void run_wo_sample_tasks(LAS unsigned char* lds, unsigned char* ws) {
;     const int t = bidx(); OneUnit S; S.valid = t < 64; const int u = (t >> 2) & 15, sl = t & 3; S.pm = 64 + (u >> 2); S.pn = u & 3;
;     pg8::Gemm g; g.A = (const bf16_t*)(ws + OFF_A) + sl * 256; g.Bt = (const bf16_t*)(ws + OFF_WO) + sl * 256; g.M = T_ALL; g.N = 1024; g.K = 256; g.ld = 1024;
;     EpiPartial EA; EA.PART = (float*)(ws + OFF_GPART) + (size_t)sl * 1024 * 1024; EA.ldp = 1024;
;     pg8::gemm_phase<EpiPartial, OneUnit, false>(lds, g, S, EA, nullptr);
; __global__ void __launch_bounds__(512, 2) mega_fwd(Params prm) {
;     ...
;         case 11: { GEMM_PRO; EpiResid E; E.X = p.out; E.XB = XB; E.rowss_out = rs_ffn; E.Xp0 = l == 0 ? INP(p, 0) : nullptr; E.Xs0 = l == 0 ? INP(p, 1) : nullptr;
;                    run_gemm(lds, (const bf16_t*)(ws + OFF_A), (const bf16_t*)(ws + OFF_WO), 1024, 1024, E, T_P);
;                    run_wo_sample_tasks(lds, ws);
;                    xcd_barrier(xb);
;                    finalize_sample(p, rs_ffn, OFF_GPART, 4, l == 0 ? INP(p, 1) : nullptr); } break;
.LBB0_129:
	s_add_u32 s60, s10, 0x5500000
	s_addc_u32 s61, s46, 0
	s_add_u32 s62, s10, 0xe00000
	s_addc_u32 s63, s46, 0
	s_and_b64 s[2:3], s[34:35], exec
	s_mov_b32 s2, 0x33000
	s_cselect_b32 s2, s2, 0x11000
	s_add_u32 s2, s10, s2
	s_addc_u32 s3, s46, 0
	s_add_u32 s2, s2, 0x2060000
	s_addc_u32 s3, s3, 0
	s_cmp_gt_i32 s90, 63
	s_cbranch_scc1 .Lp11_main
	v_writelane_b32 v255, s0, 0
	v_writelane_b32 v255, s1, 1
	v_writelane_b32 v255, s4, 2
	v_writelane_b32 v255, s5, 3
	v_writelane_b32 v255, s6, 4
	v_writelane_b32 v255, s7, 5
	v_writelane_b32 v255, s20, 6
	v_writelane_b32 v255, s22, 7
	v_writelane_b32 v255, s24, 8
	v_writelane_b32 v255, s25, 9
	v_writelane_b32 v255, s26, 10
	v_writelane_b32 v255, s27, 11
	v_writelane_b32 v255, s30, 12
	v_writelane_b32 v255, s36, 13
	v_writelane_b32 v255, s42, 14
	v_writelane_b32 v255, s43, 15
	v_writelane_b32 v255, s47, 16
	v_writelane_b32 v255, s53, 17
	v_writelane_b32 v255, s65, 18
	v_writelane_b32 v255, s60, 19
	v_writelane_b32 v255, s61, 20
	v_writelane_b32 v255, s62, 21
	v_writelane_b32 v255, s63, 22
	v_writelane_b32 v255, s2, 23
	v_writelane_b32 v255, s3, 24
	s_mov_b32 s0, 1
	v_writelane_b32 v242, s0, 61
	s_branch .LBB0_209
.Lp11_back:
	s_mov_b32 s0, 2
	v_writelane_b32 v242, s0, 61
	v_readlane_b32 s1, v255, 1
	v_readlane_b32 s4, v255, 2
	v_readlane_b32 s5, v255, 3
	v_readlane_b32 s6, v255, 4
	v_readlane_b32 s7, v255, 5
	v_readlane_b32 s20, v255, 6
	v_readlane_b32 s22, v255, 7
	v_readlane_b32 s24, v255, 8
	v_readlane_b32 s25, v255, 9
	v_readlane_b32 s26, v255, 10
	v_readlane_b32 s27, v255, 11
	v_readlane_b32 s30, v255, 12
	v_readlane_b32 s36, v255, 13
	v_readlane_b32 s42, v255, 14
	v_readlane_b32 s43, v255, 15
	v_readlane_b32 s47, v255, 16
	v_readlane_b32 s53, v255, 17
	v_readlane_b32 s65, v255, 18
	v_readlane_b32 s60, v255, 19
	v_readlane_b32 s61, v255, 20
	v_readlane_b32 s62, v255, 21
	v_readlane_b32 s63, v255, 22
	v_readlane_b32 s2, v255, 23
	v_readlane_b32 s3, v255, 24
	v_readlane_b32 s0, v255, 0
	v_mov_b32_e32 v9, v184
	s_branch .Lp11_main
.Lp11_skipB:
	s_mov_b32 s0, 0
	v_writelane_b32 v242, s0, 61
	s_branch .LBB0_217
.Lp11_main:
	s_andn2_b64 vcc, exec, s[6:7]
	s_cbranch_vccnz .LBB0_209
	v_ashrrev_i32_e32 v1, 31, v9
	v_lshrrev_b32_e32 v1, 26, v1
	v_add_u32_e32 v1, v9, v1
	v_ashrrev_i32_e32 v8, 6, v1
	v_bfe_i32 v1, v9, 27, 1
	v_lshlrev_b32_e32 v0, 4, v9
	v_lshrrev_b32_e32 v1, 22, v1
	v_add_u32_e32 v1, v0, v1
	v_and_b32_e32 v1, 0xfffffc00, v1
	v_sub_u32_e32 v1, v0, v1
	v_lshrrev_b32_e32 v2, 4, v1
	v_bitop3_b32 v1, v2, v1, 32 bitop3:0x6c
	v_ashrrev_i32_e32 v3, 31, v1
	v_lshrrev_b32_e32 v3, 26, v3
	v_add_u32_e32 v3, v1, v3
	v_lshlrev_b32_e32 v2, 3, v8
	v_ashrrev_i32_e32 v10, 6, v3
	v_and_b32_e32 v3, 0xc0, v3
	v_and_b32_e32 v2, 0x1ffff0, v2
	v_lshlrev_b32_e32 v4, 5, v8
	v_sub_u32_e32 v1, v1, v3
	v_add_u32_e32 v2, v10, v2
	v_and_b32_e32 v11, 32, v4
	v_ashrrev_i16_sdwa v1, v188, sext(v1) dst_sel:DWORD dst_unused:UNUSED_PAD src0_sel:DWORD src1_sel:BYTE_0
	s_waitcnt lgkmcnt(0)
	v_bfe_i32 v12, v1, 0, 16
	v_lshl_or_b32 v1, v2, 10, v11
	v_add_u32_e32 v0, 0x2000, v0
	v_add_lshl_u32 v148, v1, v12, 1
	v_ashrrev_i32_e32 v1, 31, v0
	v_lshrrev_b32_e32 v1, 22, v1
	v_add_u32_e32 v1, v0, v1
	v_ashrrev_i32_e32 v13, 10, v1
	v_mul_i32_i24_e32 v1, 0x400, v13
	v_sub_u32_e32 v0, v0, v1
	v_lshrrev_b32_e32 v1, 4, v0
	v_bitop3_b32 v0, v1, v0, 32 bitop3:0x6c
	v_ashrrev_i32_e32 v2, 31, v0
	v_lshrrev_b32_e32 v2, 26, v2
	s_ashr_i32 s7, s53, 6
	s_ashr_i32 s31, s30, 31
	s_ashr_i32 s37, s36, 31
	s_ashr_i32 s6, s53, 8
	v_add_u32_e32 v2, v0, v2
	s_lshl_b32 s64, s7, 10
	s_lshl_b64 s[12:13], s[30:31], 19
	s_lshl_b64 s[14:15], s[36:37], 19
	v_lshlrev_b32_e32 v1, 3, v13
	v_ashrrev_i32_e32 v14, 6, v2
	v_and_b32_e32 v2, 0xc0, v2
	s_add_u32 s48, s62, s14
	v_and_b32_e32 v1, 0x1ffff0, v1
	v_lshlrev_b32_e32 v3, 5, v13
	v_sub_u32_e32 v0, v0, v2
	s_addc_u32 s49, s63, s15
	s_add_i32 s37, s64, 0
	v_add_u32_e32 v1, v14, v1
	v_and_b32_e32 v15, 32, v3
	v_ashrrev_i16_sdwa v0, v188, sext(v0) dst_sel:DWORD dst_unused:UNUSED_PAD src0_sel:DWORD src1_sel:BYTE_0
	s_add_i32 m0, s37, 0x10000
	v_bfe_i32 v16, v0, 0, 16
	v_lshl_or_b32 v0, v1, 10, v15
	global_load_lds_dwordx4 v148, s[48:49]
	s_add_i32 m0, s37, 0x12000
	v_add_lshl_u32 v150, v0, v16, 1
	s_add_u32 s44, s60, s12
	s_mov_b32 s75, s65
	global_load_lds_dwordx4 v150, s[48:49]
	s_addc_u32 s45, s61, s13
	s_mov_b32 m0, s37
	s_add_i32 s65, s37, 0x2000
	global_load_lds_dwordx4 v148, s[44:45]
	s_mov_b32 m0, s65
	s_add_u32 s12, s48, 0x40000
	global_load_lds_dwordx4 v150, s[44:45]
	s_addc_u32 s13, s49, 0
	s_add_i32 m0, s37, 0x14000
	v_mov_b32_e32 v149, v129
	global_load_lds_dwordx4 v148, s[12:13]
	s_add_i32 m0, s37, 0x16000
	v_mov_b32_e32 v151, v129
	global_load_lds_dwordx4 v150, s[12:13]
	s_add_u32 s12, s44, 0x40000
	s_addc_u32 s13, s45, 0
	s_add_i32 s76, s37, 0x4000
	s_mov_b32 m0, s76
	s_add_i32 s77, s37, 0x6000
	global_load_lds_dwordx4 v148, s[12:13]
	s_mov_b32 m0, s77
	v_lshl_add_u64 v[6:7], s[48:49], 0, v[148:149]
	global_load_lds_dwordx4 v150, s[12:13]
	v_lshl_add_u64 v[4:5], s[48:49], 0, v[150:151]
	v_lshl_add_u64 v[2:3], s[44:45], 0, v[148:149]
	s_cmp_lg_u32 s6, 1
	v_lshl_add_u64 v[0:1], s[44:45], 0, v[150:151]
	s_cbranch_scc1 .LBB0_132
	s_barrier

; __device__ __forceinline__ int bidx() { int b = blockIdx.x; asm volatile("" : "+s"(b)); return b; }
; __device__ __forceinline__ void run_wo_sample_tasks(LAS unsigned char* lds, unsigned char* ws) {
;     const int t = bidx(); OneUnit S; S.valid = t < 64; const int u = (t >> 2) & 15, sl = t & 3; S.pm = 64 + (u >> 2); S.pn = u & 3;
;     pg8::Gemm g; g.A = (const bf16_t*)(ws + OFF_A) + sl * 256; g.Bt = (const bf16_t*)(ws + OFF_WO) + sl * 256; g.M = T_ALL; g.N = 1024; g.K = 256; g.ld = 1024;
;     EpiPartial EA; EA.PART = (float*)(ws + OFF_GPART) + (size_t)sl * 1024 * 1024; EA.ldp = 1024;
;     pg8::gemm_phase<EpiPartial, OneUnit, false>(lds, g, S, EA, nullptr);
.LBB0_209:
	v_readlane_b32 s0, v242, 61
	s_cmp_eq_u32 s0, 2
	s_cbranch_scc1 .Lp11_skipB
	s_mov_b32 s0, s90
	v_mov_b32_e32 v0, v184
	s_cmp_gt_i32 s0, 63
	s_nop 0
	v_readfirstlane_b32 s40, v0
	s_cbranch_scc1 .LBB0_217
	s_waitcnt lgkmcnt(0)
	v_lshlrev_b32_e32 v1, 4, v0
	v_add_u32_e32 v2, 0x2000, v1
	v_ashrrev_i32_e32 v3, 31, v2
	v_lshrrev_b32_e32 v3, 22, v3
	v_add_u32_e32 v3, v2, v3
	v_ashrrev_i32_e32 v3, 10, v3
	v_mul_i32_i24_e32 v4, 0x400, v3
	v_sub_u32_e32 v2, v2, v4
	v_lshrrev_b32_e32 v4, 4, v2
	v_bitop3_b32 v2, v4, v2, 32 bitop3:0x6c
	v_ashrrev_i32_e32 v4, 31, v2
	v_lshrrev_b32_e32 v4, 26, v4
	v_add_u32_e32 v4, v2, v4
	v_lshrrev_b32_e32 v5, 6, v4
	v_lshlrev_b32_e32 v6, 3, v3
	v_and_b32_e32 v4, 0xc0, v4
	v_and_b32_e32 v6, 0x1ffff0, v6
	v_lshlrev_b32_e32 v3, 5, v3
	v_sub_u32_e32 v2, v2, v4
	v_add_u32_e32 v5, v5, v6
	v_and_b32_e32 v3, 32, v3
	v_ashrrev_i16_sdwa v2, v188, sext(v2) dst_sel:DWORD dst_unused:UNUSED_PAD src0_sel:DWORD src1_sel:BYTE_0
	v_lshl_or_b32 v3, v5, 10, v3
	v_bfe_i32 v2, v2, 0, 16
	v_add_lshl_u32 v148, v3, v2, 1
	v_bfe_i32 v2, v0, 27, 1
	v_lshrrev_b32_e32 v2, 22, v2
	v_add_u32_e32 v2, v1, v2
	v_and_b32_e32 v2, 0xfffffc00, v2
	v_sub_u32_e32 v1, v1, v2
	v_lshrrev_b32_e32 v2, 4, v1
	s_and_b32 s43, s0, 3
	s_bfe_u32 s1, s0, 0x20004
	s_ashr_i32 s12, s40, 6
	v_bitop3_b32 v1, v2, v1, 32 bitop3:0x6c
	v_ashrrev_i32_e32 v4, 31, v0
	s_or_b32 s42, s1, 64
	s_bfe_u32 s41, s0, 0x20002
	s_ashr_i32 s13, s40, 8
	s_lshl_b32 s44, s12, 10
	s_lshl_b32 s0, s43, 9
	v_ashrrev_i32_e32 v2, 31, v1
	v_lshrrev_b32_e32 v4, 26, v4
	s_add_u32 s1, s62, s0
	v_lshrrev_b32_e32 v2, 26, v2
	v_add_u32_e32 v4, v0, v4
	s_addc_u32 s4, s63, 0
	v_add_u32_e32 v2, v1, v2
	v_ashrrev_i32_e32 v4, 6, v4
	s_add_u32 s5, s60, s0
	v_lshrrev_b32_e32 v3, 6, v2
	v_lshlrev_b32_e32 v5, 3, v4
	v_and_b32_e32 v2, 0xc0, v2
	s_addc_u32 s6, s61, 0
	v_and_b32_e32 v5, 0x1ffff0, v5
	v_lshlrev_b32_e32 v4, 5, v4
	v_sub_u32_e32 v1, v1, v2
	s_lshl_b32 s7, s42, 19
	s_lshl_b32 s0, s41, 19
	v_add_u32_e32 v3, v3, v5
	v_and_b32_e32 v4, 32, v4
	v_ashrrev_i16_sdwa v1, v188, sext(v1) dst_sel:DWORD dst_unused:UNUSED_PAD src0_sel:DWORD src1_sel:BYTE_0
	s_add_u32 s0, s1, s0
	v_lshl_or_b32 v3, v3, 10, v4
	v_bfe_i32 v1, v1, 0, 16
	s_addc_u32 s1, s4, 0
	s_add_i32 s45, s44, 0
	v_add_lshl_u32 v128, v3, v1, 1
	s_add_i32 m0, s45, 0x10000
	s_mov_b32 s64, s65
	global_load_lds_dwordx4 v128, s[0:1]
	s_add_i32 m0, s45, 0x12000
	s_add_u32 s4, s5, s7
	global_load_lds_dwordx4 v148, s[0:1]
	s_addc_u32 s5, s6, 0
	s_mov_b32 m0, s45
	s_add_i32 s47, s45, 0x2000
	global_load_lds_dwordx4 v128, s[4:5]
	s_mov_b32 m0, s47
	s_add_u32 s6, s0, 0x40000
	global_load_lds_dwordx4 v148, s[4:5]
	s_addc_u32 s7, s1, 0
	s_add_i32 m0, s45, 0x14000
	s_nop 0
	global_load_lds_dwordx4 v128, s[6:7]
	s_add_i32 m0, s45, 0x16000
	s_nop 0
	global_load_lds_dwordx4 v148, s[6:7]
	s_add_u32 s6, s4, 0x40000
	s_addc_u32 s7, s5, 0
	s_add_i32 s48, s45, 0x4000
	s_mov_b32 m0, s48
	s_add_i32 s49, s45, 0x6000
	global_load_lds_dwordx4 v128, s[6:7]
	s_mov_b32 m0, s49
	s_cmp_lg_u32 s13, 1
	global_load_lds_dwordx4 v148, s[6:7]
	s_cbranch_scc1 .LBB0_212
	s_barrier

; __device__ __forceinline__ void xcd_barrier(const XcdBarrier& b) {
;     asm volatile("s_waitcnt vmcnt(0)" ::: "memory");
;     __syncthreads();
;     if (threadIdx.x == 0) {
;         unsigned* bar = b.bar;
;         __builtin_amdgcn_s_waitcnt(0);
;         unsigned nloc = b.st[0], nx = b.st[1];
;         if (nloc == 0u) { xcd_barrier_complete(bar, b.x, nloc, nx); b.st[0] = nloc; b.st[1] = nx; }
.LBB0_217:
	v_readlane_b32 s0, v242, 61
	s_cmp_eq_u32 s0, 1
	s_cbranch_scc1 .Lp11_back
	s_waitcnt vmcnt(0)
	s_waitcnt vmcnt(0) lgkmcnt(0)
	s_barrier
	s_and_saveexec_b64 s[0:1], s[94:95]
	v_readlane_b32 s46, v242, 24
	v_readlane_b32 s47, v242, 25
	s_mov_b32 s62, 0x1800000
	s_mov_b64 s[36:37], 0
	s_cbranch_execz .LBB0_269
	v_readlane_b32 s4, v242, 16
	s_waitcnt vmcnt(0) expcnt(0) lgkmcnt(0)
	s_nop 0
	v_mov_b32_e32 v0, s4
	ds_read_b32 v2, v0
	v_readlane_b32 s4, v242, 17
	s_waitcnt lgkmcnt(0)
	v_cmp_ne_u32_e32 vcc, 0, v2
	v_mov_b32_e32 v0, s4
	ds_read_b32 v0, v0
	s_cbranch_vccnz .LBB0_233
	s_mov_b32 s10, 1
	s_branch .LBB0_221
